# baseline (speedup 1.0000x reference)
; __device__ __forceinline__ void scan_pc(const Params& p, int j, const u16* R, const u16* K, const u16* V, u16* Y, u16* YB) {
;     ...
;     u16* Yw = (ymode == 2) ? YB - (size_t)NPROMPT * CM : Y;
;     int ch = h * 64 + w4 * 16 + fr;
;     unsigned cho = (unsigned)ch * 4u;
;     float w0c = ldo<float>(w0, cho), a0c = ldo<float>(a0, cho), kac = ldo<float>(kap, cho), kkme = ldo<float>(kkp, cho), rkc = ldo<float>(rkp, cho);
;     bf16x8* LB = reinterpret_cast<bf16x8*>(shm + 4 * IMG_ELEMS + 2 * MM_ELEMS) + wv * 256 + lane;
;     if (prod) {
;       _Pragma("unroll") for (int ks = 0; ks < 2; ++ks) { LB[ks * 64] = ldo<bf16x8>(w2T, (unsigned)(ch * 64 + ks * 32 + fq * 8) * 2u); LB[(2 + ks) * 64] = ldo<bf16x8>(a2T, (unsigned)(ch * 64 + ks * 32 + fq * 8) * 2u); }
;     }
;     f32x4 Z[4]; s4 Zb[4];
;     _Pragma("unroll") for (int kb = 0; kb < 4; ++kb) { Z[kb] = (f32x4){0.f, 0.f, 0.f, 0.f}; Zb[kb] = (s4){0, 0, 0, 0}; }
;     struct Raw { bf16x8 rw[2], ra[2]; u16 rk[4], rr[4], rv[4]; };
;     Raw r0, r1;
;     float yo[4] = {0.f, 0.f, 0.f, 0.f};
;     int tdir = (d == 0) ? 1 : -1, t00 = (d == 0) ? base : base + T - 1;
;     auto tokof = [&](int c, int s_) { return t00 + tdir * (c * 16 + s_); };
;     int offA0 = (t00 + tdir * fr) * 128 + fq * 16, dA = tdir * 2048;
;     int offK0[4], dK = tdir * 32768;
;     _Pragma("unroll") for (int jj = 0; jj < 4; ++jj) offK0[jj] = ((t00 + tdir * (fq * 4 + jj)) * 1024 + (h * 64 + w4 * 16 + fr)) * 2;
.LBB0_2716:
	s_or_b64 exec, exec, s[20:21]
	s_lshr_b32 s2, s2, 4
	s_cmp_eq_u32 s29, 2
	v_readlane_b32 s20, v246, 46
	s_cselect_b32 s71, s20, s67
	v_readlane_b32 s20, v246, 45
	s_cselect_b32 s70, s20, s66
	s_cmp_eq_u32 s29, 1
	s_cselect_b64 s[20:21], -1, 0
	s_lshl_b32 s26, s30, 2
	s_lshl_b32 s27, s88, 1
	s_add_i32 s33, s26, s27
	s_lshl_b32 s27, s30, 7
	s_mul_i32 s26, s31, 0x11800
	v_add3_u32 v166, v149, v46, s27
	v_add_u32_e32 v167, s26, v166
	s_mul_i32 s26, s31, 0x11000
	v_add_u32_e32 v168, s26, v166
	s_mul_i32 s26, s31, 0x10800
	v_add_u32_e32 v169, s26, v166
	s_mul_i32 s26, s31, 0x9800
	v_mul_i32_i24_e32 v32, s31, v148
	v_add_u32_e32 v171, s26, v166
	s_mul_i32 s26, s31, 0x9000
	v_add_lshl_u32 v128, s62, v32, 6
	s_lshl_b32 s64, s31, 16
	v_add_u32_e32 v172, s26, v166
	s_mul_i32 s26, s31, 0x8800
	v_mul_i32_i24_e32 v32, s31, v150
	v_mov_b32_e32 v40, 0
	s_mov_b32 s3, 2
	s_mov_b32 s28, 1
	s_add_i32 s29, s2, -1
	s_waitcnt vmcnt(1)
	v_mov_b32_e32 v77, v76
	v_mov_b32_e32 v75, v74
	s_waitcnt vmcnt(0)
	v_mov_b32_e32 v79, v78
	v_add3_u32 v170, s64, v46, v44
	v_add_u32_e32 v173, s26, v166
	v_add3_u32 v174, s8, v46, v44
	v_add_lshl_u32 v175, s62, v32, 6
	v_add_u32_e32 v176, v48, v44
	v_add_u32_e32 v177, v47, v44
	v_add_u32_e32 v178, v45, v44
	s_mov_b32 s65, 3
	s_mov_b32 s74, 0
	s_mov_b64 s[68:69], 0
	v_mov_b32_e32 v90, 0
	v_mov_b32_e32 v48, 0
	v_mov_b32_e32 v49, 0
	v_mov_b32_e32 v52, 0
	v_mov_b32_e32 v53, 0
	v_mov_b32_e32 v56, 0
	v_mov_b32_e32 v57, 0
	v_mov_b32_e32 v64, 0
	v_mov_b32_e32 v65, 0
	v_mov_b32_e32 v238, 0
	v_mov_b32_e32 v239, 0
	v_mov_b32_e32 v240, 0
	v_mov_b32_e32 v241, 0
	v_mov_b32_e32 v242, 0
	v_mov_b32_e32 v243, 0
	v_mov_b32_e32 v244, 0
	v_mov_b32_e32 v245, 0
	v_mov_b32_e32 v41, v40
	v_mov_b32_e32 v42, v40
	v_mov_b32_e32 v43, v40
	v_mov_b32_e32 v44, v40
	v_mov_b32_e32 v45, v40
	v_mov_b32_e32 v46, v40
	v_mov_b32_e32 v47, v40
	v_mov_b32_e32 v32, v40
	v_mov_b32_e32 v33, v40
	v_mov_b32_e32 v34, v40
	v_mov_b32_e32 v35, v40
	v_mov_b32_e32 v36, v40
	v_mov_b32_e32 v37, v40
	v_mov_b32_e32 v38, v40
	v_mov_b32_e32 v39, v40
	v_readlane_b32 s88, v246, 15
	s_waitcnt lgkmcnt(0)
	s_barrier
	s_branch .LBB0_2720

; #define MFMA4(a, b, c) __builtin_amdgcn_mfma_f32_16x16x16bf16_1k(a, b, c, 0, 0, 0)
; __device__ __forceinline__ s4 pack4v(f32x4 v) { return pack4(v[0], v[1], v[2], v[3]); }
; __device__ __forceinline__ void scan_pc(const Params& p, int j, const u16* R, const u16* K, const u16* V, u16* Y, u16* YB) {
;     ...
;       const u16* IMG = shm + (c % 3) * IMG_ELEMS;
;       const u16* MM = shm + 4 * IMG_ELEMS + (c & 1) * MM_ELEMS;
;       s4 vb = *reinterpret_cast<const s4*>(IMG + IMG_VT + (w4 * 16 + fr) * XK_LD + fq * 4);
;       f32x4 z4 = {0.f, 0.f, 0.f, 0.f};
;       const float* PL = reinterpret_cast<const float*>(IMG + IMG_PL);
;       float4 iv = *reinterpret_cast<const float4*>(PL + 192 + fq * 4);
;       f32x4 rhs = z4;
;       f32x4 y = MFMA4(*reinterpret_cast<const s4*>(MM + (3 * 16 + fr) * XK_LD + fq * 4), vb, z4);
;       _Pragma("unroll") for (int kb = 0; kb < 4; ++kb) {
;         rhs = MFMA4(*reinterpret_cast<const s4*>(IMG + (0 * 16 + fr) * XT_LD + kb * 16 + fq * 4), Zb[kb], rhs);
;         y = MFMA4(*reinterpret_cast<const s4*>(IMG + (1 * 16 + fr) * XT_LD + kb * 16 + fq * 4), Zb[kb], y);
;       }
;       rhs[0] *= iv.x; rhs[1] *= iv.y; rhs[2] *= iv.z; rhs[3] *= iv.w;
;       rhs = MFMA4(*reinterpret_cast<const s4*>(MM + (1 * 16 + fr) * XK_LD + fq * 4), vb, rhs);
;       f32x4 u = MFMA4(*reinterpret_cast<const s4*>(MM + (0 * 16 + fr) * XK_LD + fq * 4), pack4v(rhs), z4);
;       y = MFMA4(*reinterpret_cast<const s4*>(MM + (2 * 16 + fr) * XK_LD + fq * 4), pack4v(u), y);
.LBB0_2720:
	s_mul_hi_u32 s26, s28, 0xaaaaaaab
	s_lshr_b32 s26, s26, 1
	s_mul_i32 s26, s26, 3
	s_sub_i32 s75, 1, s26
	v_lshlrev_b32_e32 v179, 1, v97
	s_and_saveexec_b64 s[26:27], s[10:11]
	s_xor_b64 s[26:27], exec, s[26:27]
	s_cbranch_execz .LBB0_2739
	s_mov_b32 s30, 0xaaaaaaab
	v_mul_hi_u32 v50, v90, s30
	v_lshrrev_b32_e32 v50, 1, v50
	v_mad_u64_u32 v[50:51], s[30:31], v50, -3, v[90:91]
	v_mad_u32_u24 v58, v50, s80, 0
	v_add3_u32 v50, v58, v127, v179
	ds_read_b64 v[70:71], v50 offset:14336
	v_lshl_add_u32 v50, v97, 2, v58
	ds_read_b128 v[66:69], v50 offset:17664
	v_add3_u32 v50, v58, v146, v179
	ds_read2_b64 v[60:63], v145 offset0:160 offset1:240
	ds_read2_b64 v[194:197], v50 offset1:4
	v_add_u32_e32 v59, 0x800, v50
	ds_read2_b64 v[202:205], v59 offset0:32 offset1:36
	s_waitcnt lgkmcnt(2)
	v_mfma_f32_16x16x16_bf16 v[92:95], v[62:63], v[70:71], 0
	v_add3_u32 v91, v58, v144, v133
	v_add_u32_e32 v193, 0x2c00, v91
	v_readlane_b32 s76, v247, 14
	s_waitcnt lgkmcnt(1)
	v_mfma_f32_16x16x32_bf16 v[226:229], v[194:197], v[238:241], 0
	v_readlane_b32 s77, v247, 15
	v_readlane_b32 s78, v247, 16
	v_readlane_b32 s79, v247, 17
	s_waitcnt lgkmcnt(0)
	v_mfma_f32_16x16x32_bf16 v[62:65], v[202:205], v[238:241], v[92:95]
	s_mov_b32 s77, s76
	s_mov_b32 s78, s76
	s_mov_b32 s79, s76
	ds_read2_b64 v[194:197], v50 offset0:8 offset1:12
	v_add_u32_e32 v50, 0x2000, v91
	v_writelane_b32 v247, s76, 14
	s_waitcnt lgkmcnt(0)
	v_mfma_f32_16x16x32_bf16 v[92:95], v[194:197], v[242:245], v[226:229]
	ds_read2_b64 v[198:201], v145 offset1:80
	v_writelane_b32 v247, s77, 15
	v_writelane_b32 v247, s78, 16
	ds_read2_b64 v[194:197], v50 offset0:128 offset1:208
	v_writelane_b32 v247, s79, 17
	s_nop 4
	v_mul_f32_e64 v94, v68, v94
	v_mul_f32_e64 v95, v69, v95
	v_pk_mul_f32 v[92:93], v[66:67], v[92:93]
	s_waitcnt lgkmcnt(1)
	s_nop 0
	v_mfma_f32_16x16x16_bf16 v[92:95], v[200:201], v[70:71], v[92:95]
	s_nop 7
	v_cvt_pk_bf16_f32 v50, v92, v93
	v_cvt_pk_bf16_f32 v51, v94, v95
	s_nop 1
	v_mfma_f32_16x16x16_bf16 v[92:95], v[198:199], v[50:51], 0
	ds_read2_b64 v[198:201], v59 offset0:40 offset1:44
	s_nop 6
	v_pk_mul_f32 v[50:51], v[66:67], v[92:93]
	v_pk_mul_f32 v[54:55], v[68:69], v[94:95]
	ds_read2_b64 v[66:69], v193 offset0:64 offset1:144
	v_cvt_pk_bf16_f32 v180, v50, v51
	v_cvt_pk_bf16_f32 v181, v54, v55
	s_waitcnt lgkmcnt(1)
	v_mfma_f32_16x16x32_bf16 v[234:237], v[198:201], v[242:245], v[62:65]
	v_add_u32_e32 v193, v58, v112
	v_add_u32_e32 v54, 0x2800, v91
	v_cvt_pk_bf16_f32 v202, v92, v93
	v_mfma_f32_16x16x16_bf16 v[40:43], v[194:195], v[180:181], v[40:43]
	v_cvt_pk_bf16_f32 v203, v94, v95
	v_mfma_f32_16x16x16_bf16 v[194:197], v[196:197], v[180:181], v[44:47]
	ds_read_b128 v[56:59], v193 offset:16896
	s_nop 1
	ds_read_b128 v[44:47], v193 offset:16960
	s_waitcnt lgkmcnt(2)
	v_mfma_f32_16x16x16_bf16 v[40:43], v[66:67], v[70:71], v[40:43]
	ds_read2_b64 v[64:67], v54 offset0:32 offset1:112
	v_add_u32_e32 v54, 0x3000, v91
	v_add_u32_e32 v91, s74, v166
	ds_read2_b64 v[198:201], v54 offset0:96 offset1:176
	s_nop 1
	ds_read_b128 v[52:55], v193 offset:17024
	ds_read_b128 v[48:51], v193 offset:17088
	v_mfma_f32_16x16x16_bf16 v[92:95], v[60:61], v[202:203], v[234:237]
	s_waitcnt lgkmcnt(3)
	v_mfma_f32_16x16x16_bf16 v[32:35], v[64:65], v[180:181], v[32:35]
	v_mfma_f32_16x16x16_bf16 v[36:39], v[66:67], v[180:181], v[36:39]
	s_andn2_b64 vcc, exec, s[20:21]
	s_cbranch_vccnz .Lyold_done_a
	s_waitcnt vmcnt(0)
	v_lshlrev_b32_e32 v87, 16, v230
	v_lshlrev_b32_e32 v88, 16, v231
	v_lshlrev_b32_e32 v86, 16, v232
	v_lshlrev_b32_e32 v89, 16, v233

; __device__ __forceinline__ s4 pack4v(f32x4 v) { return pack4(v[0], v[1], v[2], v[3]); }
; __device__ __forceinline__ void scan_pc(const Params& p, int j, const u16* R, const u16* K, const u16* V, u16* Y, u16* YB) {
;     ...
;         float4 pl = *reinterpret_cast<const float4*>(PL + kb * 16 + fq * 4);
;         Z[kb][0] *= pl.x; Z[kb][1] *= pl.y; Z[kb][2] *= pl.z; Z[kb][3] *= pl.w;
;         Zb[kb] = pack4v(Z[kb]);
.LBB0_2738:
	s_or_b64 exec, exec, s[62:63]
	v_pk_mul_f32 v[40:41], v[40:41], v[56:57]
	v_pk_mul_f32 v[42:43], v[42:43], v[58:59]
	v_pk_mul_f32 v[44:45], v[60:61], v[44:45]
	v_pk_mul_f32 v[46:47], v[62:63], v[46:47]
	s_waitcnt lgkmcnt(1)
	v_pk_mul_f32 v[32:33], v[32:33], v[52:53]
	v_pk_mul_f32 v[34:35], v[34:35], v[54:55]
	s_waitcnt lgkmcnt(0)
	v_pk_mul_f32 v[36:37], v[36:37], v[48:49]
	v_pk_mul_f32 v[38:39], v[38:39], v[50:51]
	v_cvt_pk_bf16_f32 v238, v40, v41
	v_cvt_pk_bf16_f32 v239, v42, v43
	v_cvt_pk_bf16_f32 v240, v44, v45
	v_cvt_pk_bf16_f32 v241, v46, v47
	v_cvt_pk_bf16_f32 v242, v32, v33
	v_cvt_pk_bf16_f32 v243, v34, v35
	v_cvt_pk_bf16_f32 v244, v36, v37
	v_cvt_pk_bf16_f32 v245, v38, v39

; #define MFMA4(a, b, c) __builtin_amdgcn_mfma_f32_16x16x16bf16_1k(a, b, c, 0, 0, 0)
; __device__ __forceinline__ s4 pack4v(f32x4 v) { return pack4(v[0], v[1], v[2], v[3]); }
; __device__ __forceinline__ void scan_pc(const Params& p, int j, const u16* R, const u16* K, const u16* V, u16* Y, u16* YB) {
;     ...
;       const u16* IMG = shm + (c % 3) * IMG_ELEMS;
;       const u16* MM = shm + 4 * IMG_ELEMS + (c & 1) * MM_ELEMS;
;       s4 vb = *reinterpret_cast<const s4*>(IMG + IMG_VT + (w4 * 16 + fr) * XK_LD + fq * 4);
;       f32x4 z4 = {0.f, 0.f, 0.f, 0.f};
;       const float* PL = reinterpret_cast<const float*>(IMG + IMG_PL);
;       float4 iv = *reinterpret_cast<const float4*>(PL + 192 + fq * 4);
;       f32x4 rhs = z4;
;       f32x4 y = MFMA4(*reinterpret_cast<const s4*>(MM + (3 * 16 + fr) * XK_LD + fq * 4), vb, z4);
;       _Pragma("unroll") for (int kb = 0; kb < 4; ++kb) {
;         rhs = MFMA4(*reinterpret_cast<const s4*>(IMG + (0 * 16 + fr) * XT_LD + kb * 16 + fq * 4), Zb[kb], rhs);
;         y = MFMA4(*reinterpret_cast<const s4*>(IMG + (1 * 16 + fr) * XT_LD + kb * 16 + fq * 4), Zb[kb], y);
;       }
;       rhs[0] *= iv.x; rhs[1] *= iv.y; rhs[2] *= iv.z; rhs[3] *= iv.w;
;       rhs = MFMA4(*reinterpret_cast<const s4*>(MM + (1 * 16 + fr) * XK_LD + fq * 4), vb, rhs);
;       f32x4 u = MFMA4(*reinterpret_cast<const s4*>(MM + (0 * 16 + fr) * XK_LD + fq * 4), pack4v(rhs), z4);
;       y = MFMA4(*reinterpret_cast<const s4*>(MM + (2 * 16 + fr) * XK_LD + fq * 4), pack4v(u), y);
.LBB0_2745:
	s_or_b64 exec, exec, s[26:27]
	s_waitcnt lgkmcnt(0)
	s_barrier
	s_and_saveexec_b64 s[26:27], s[10:11]
	s_xor_b64 s[26:27], exec, s[26:27]
	s_cbranch_execz .LBB0_2764
	v_add_u32_e32 v50, s75, v90
	v_mad_u32_u24 v91, v50, s80, 0
	v_add3_u32 v51, v91, v146, v179
	ds_read2_b64 v[66:69], v147 offset0:160 offset1:240
	ds_read2_b64 v[92:95], v51 offset1:4
	v_add3_u32 v50, v91, v127, v179
	ds_read_b64 v[180:181], v50 offset:14336
	v_lshl_add_u32 v50, v97, 2, v91
	ds_read_b128 v[58:61], v50 offset:17664
	v_add_u32_e32 v50, 0x800, v51
	ds_read2_b64 v[198:201], v50 offset0:32 offset1:36
	s_waitcnt lgkmcnt(2)
	v_mfma_f32_16x16x16_bf16 v[68:71], v[68:69], v[180:181], 0
	v_add3_u32 v193, v91, v144, v133
	v_add_u32_e32 v202, 0x2c00, v193
	v_add_u32_e32 v91, v91, v112
	v_mfma_f32_16x16x32_bf16 v[226:229], v[92:95], v[238:241], 0
	v_readlane_b32 s80, v247, 14
	v_readlane_b32 s81, v247, 15
	v_readlane_b32 s82, v247, 16
	s_waitcnt lgkmcnt(0)
	v_mfma_f32_16x16x32_bf16 v[198:201], v[198:201], v[238:241], v[68:71]
	v_readlane_b32 s83, v247, 17
	s_mov_b32 s81, s80
	s_mov_b32 s82, s80
	ds_read2_b64 v[92:95], v51 offset0:8 offset1:12
	v_add_u32_e32 v51, 0x2000, v193
	s_mov_b32 s83, s80
	s_waitcnt lgkmcnt(0)
	v_mfma_f32_16x16x32_bf16 v[68:71], v[92:95], v[242:245], v[226:229]
	ds_read2_b64 v[194:197], v147 offset1:80
	v_writelane_b32 v247, s80, 14
	ds_read2_b64 v[92:95], v50 offset0:40 offset1:44
	v_writelane_b32 v247, s81, 15
	v_writelane_b32 v247, s82, 16
	v_writelane_b32 v247, s83, 17
	s_nop 2
	v_pk_mul_f32 v[56:57], v[60:61], v[70:71]
	v_pk_mul_f32 v[54:55], v[58:59], v[68:69]
	ds_read2_b64 v[62:65], v51 offset0:128 offset1:208
	ds_read2_b64 v[68:71], v202 offset0:64 offset1:144
	s_waitcnt lgkmcnt(3)
	v_mfma_f32_16x16x16_bf16 v[54:57], v[196:197], v[180:181], v[54:57]
	s_movk_i32 s80, 0x4540
	s_nop 6
	v_cvt_pk_bf16_f32 v50, v54, v55
	v_cvt_pk_bf16_f32 v51, v56, v57
	s_nop 1
	v_mfma_f32_16x16x16_bf16 v[54:57], v[194:195], v[50:51], 0
	s_nop 7
	v_pk_mul_f32 v[50:51], v[58:59], v[54:55]
	v_pk_mul_f32 v[58:59], v[60:61], v[56:57]
	v_cvt_pk_bf16_f32 v202, v50, v51
	s_waitcnt lgkmcnt(2)
	v_mfma_f32_16x16x32_bf16 v[234:237], v[92:95], v[242:245], v[198:201]
	v_cvt_pk_bf16_f32 v203, v58, v59
	v_cvt_pk_bf16_f32 v204, v54, v55
	v_add_u32_e32 v54, 0x2800, v193
	s_waitcnt lgkmcnt(1)
	v_mfma_f32_16x16x16_bf16 v[40:43], v[62:63], v[202:203], v[40:43]
	v_cvt_pk_bf16_f32 v205, v56, v57
	ds_read_b128 v[60:63], v91 offset:16896
	ds_read_b128 v[56:59], v91 offset:16960
	ds_read2_b64 v[194:197], v54 offset0:32 offset1:112
	v_add_u32_e32 v54, 0x3000, v193
	ds_read2_b64 v[198:201], v54 offset0:96 offset1:176
	s_nop 0
	ds_read_b128 v[52:55], v91 offset:17024
	ds_read_b128 v[48:51], v91 offset:17088
	v_add_u32_e32 v91, s74, v174
	s_waitcnt lgkmcnt(6)
	v_mfma_f32_16x16x16_bf16 v[40:43], v[68:69], v[180:181], v[40:43]
	v_mfma_f32_16x16x16_bf16 v[66:69], v[66:67], v[204:205], v[234:237]
	v_mfma_f32_16x16x16_bf16 v[44:47], v[64:65], v[202:203], v[44:47]
	s_andn2_b64 vcc, exec, s[20:21]
	s_cbranch_vccnz .Lyold_done_b
	s_waitcnt vmcnt(0)
	v_lshlrev_b32_e32 v87, 16, v230
	v_lshlrev_b32_e32 v88, 16, v231
	v_lshlrev_b32_e32 v86, 16, v232
	v_lshlrev_b32_e32 v89, 16, v233

; __device__ __forceinline__ s4 pack4v(f32x4 v) { return pack4(v[0], v[1], v[2], v[3]); }
; __device__ __forceinline__ void scan_pc(const Params& p, int j, const u16* R, const u16* K, const u16* V, u16* Y, u16* YB) {
;     ...
;         float4 pl = *reinterpret_cast<const float4*>(PL + kb * 16 + fq * 4);
;         Z[kb][0] *= pl.x; Z[kb][1] *= pl.y; Z[kb][2] *= pl.z; Z[kb][3] *= pl.w;
;         Zb[kb] = pack4v(Z[kb]);
.LBB0_2763:
	s_or_b64 exec, exec, s[62:63]
	v_pk_mul_f32 v[40:41], v[40:41], v[60:61]
	v_pk_mul_f32 v[42:43], v[42:43], v[62:63]
	v_pk_mul_f32 v[44:45], v[44:45], v[56:57]
	v_pk_mul_f32 v[46:47], v[46:47], v[58:59]
	s_waitcnt lgkmcnt(1)
	v_pk_mul_f32 v[32:33], v[32:33], v[52:53]
	v_pk_mul_f32 v[34:35], v[34:35], v[54:55]
	s_waitcnt lgkmcnt(0)
	v_pk_mul_f32 v[36:37], v[36:37], v[48:49]
	v_pk_mul_f32 v[38:39], v[38:39], v[50:51]
	v_cvt_pk_bf16_f32 v238, v40, v41
	v_cvt_pk_bf16_f32 v239, v42, v43
	v_cvt_pk_bf16_f32 v240, v44, v45
	v_cvt_pk_bf16_f32 v241, v46, v47
	v_cvt_pk_bf16_f32 v242, v32, v33
	v_cvt_pk_bf16_f32 v243, v34, v35
	v_cvt_pk_bf16_f32 v244, v36, v37
	v_cvt_pk_bf16_f32 v245, v38, v39
